# RG-LRU pass A scan: the 32 LDS values of a sub-block fetched up front, dependent h/P chain behind counted lgkmcnt waits
# speedup vs baseline: 1.0046x; 1.0001x over previous
.LBB0_207:
	s_waitcnt lgkmcnt(0)
	ds_read_b128 v[120:123], v180 offset:11008
	s_add_i32 s43, s43, 16
	s_cmpk_lg_i32 s43, 0x80
	s_waitcnt lgkmcnt(0)
	v_lshlrev_b32_e32 v124, 16, v120
	v_and_b32_e32 v125, 0xffff0000, v120
	v_lshlrev_b32_e32 v120, 16, v121
	v_and_b32_e32 v121, 0xffff0000, v121
	v_lshlrev_b32_e32 v126, 16, v122
	v_and_b32_e32 v127, 0xffff0000, v122
	v_lshlrev_b32_e32 v122, 16, v123
	v_and_b32_e32 v123, 0xffff0000, v123
	v_pk_fma_f32 v[128:129], v[6:7], v[120:121], v[22:23]
	v_pk_fma_f32 v[130:131], v[2:3], v[122:123], v[18:19]
	ds_read_b128 v[120:123], v180 offset:11152
	v_pk_fma_f32 v[124:125], v[4:5], v[124:125], v[20:21]
	v_pk_fma_f32 v[126:127], v[0:1], v[126:127], v[16:17]
	s_waitcnt lgkmcnt(0)
	v_lshlrev_b32_e32 v132, 16, v120
	v_and_b32_e32 v133, 0xffff0000, v120
	v_lshlrev_b32_e32 v120, 16, v121
	v_and_b32_e32 v121, 0xffff0000, v121
	v_lshlrev_b32_e32 v134, 16, v122
	v_and_b32_e32 v135, 0xffff0000, v122
	v_lshlrev_b32_e32 v122, 16, v123
	v_and_b32_e32 v123, 0xffff0000, v123
	v_pk_fma_f32 v[128:129], v[14:15], v[120:121], v[128:129]
	v_pk_fma_f32 v[130:131], v[10:11], v[122:123], v[130:131]
	ds_read_b128 v[120:123], v180 offset:11296
	v_pk_fma_f32 v[124:125], v[12:13], v[132:133], v[124:125]
	v_pk_fma_f32 v[126:127], v[8:9], v[134:135], v[126:127]
	s_waitcnt lgkmcnt(0)
	v_lshlrev_b32_e32 v132, 16, v120
	v_and_b32_e32 v133, 0xffff0000, v120
	v_lshlrev_b32_e32 v120, 16, v121
	v_and_b32_e32 v121, 0xffff0000, v121
	v_lshlrev_b32_e32 v134, 16, v122
	v_and_b32_e32 v135, 0xffff0000, v122
	v_lshlrev_b32_e32 v122, 16, v123
	v_and_b32_e32 v123, 0xffff0000, v123
	v_pk_fma_f32 v[124:125], v[24:25], v[132:133], v[124:125]
	v_pk_fma_f32 v[128:129], v[26:27], v[120:121], v[128:129]
	v_pk_fma_f32 v[132:133], v[28:29], v[134:135], v[126:127]
	v_pk_fma_f32 v[126:127], v[30:31], v[122:123], v[130:131]
	ds_read_b128 v[120:123], v180 offset:11440
	s_waitcnt lgkmcnt(0)
	v_lshlrev_b32_e32 v130, 16, v120
	v_and_b32_e32 v131, 0xffff0000, v120
	v_lshlrev_b32_e32 v120, 16, v121
	v_and_b32_e32 v121, 0xffff0000, v121
	v_lshlrev_b32_e32 v134, 16, v122
	v_and_b32_e32 v135, 0xffff0000, v122
	v_lshlrev_b32_e32 v136, 16, v123
	v_and_b32_e32 v137, 0xffff0000, v123
	v_pk_fma_f32 v[122:123], v[34:35], v[120:121], v[128:129]
	v_pk_fma_f32 v[120:121], v[32:33], v[130:131], v[124:125]
	v_pk_fma_f32 v[126:127], v[38:39], v[136:137], v[126:127]
	v_pk_fma_f32 v[124:125], v[36:37], v[134:135], v[132:133]
	ds_write_b128 v179, v[120:123] offset:2304
	ds_write_b128 v179, v[124:127] offset:2320
	v_cvt_pk_bf16_f32 v120, v120, v121
	v_cvt_pk_bf16_f32 v121, v122, v123
	v_cvt_pk_bf16_f32 v122, v124, v125
	v_cvt_pk_bf16_f32 v123, v126, v127
	ds_write_b128 v180, v[120:123]
	ds_read_b128 v[120:123], v180 offset:12160
	s_waitcnt lgkmcnt(0)
	v_lshlrev_b32_e32 v124, 16, v120
	v_and_b32_e32 v125, 0xffff0000, v120
	v_lshlrev_b32_e32 v120, 16, v121
	v_and_b32_e32 v121, 0xffff0000, v121
	v_lshlrev_b32_e32 v126, 16, v122
	v_and_b32_e32 v127, 0xffff0000, v122
	v_lshlrev_b32_e32 v122, 16, v123
	v_and_b32_e32 v123, 0xffff0000, v123
	v_pk_fma_f32 v[128:129], v[6:7], v[120:121], v[22:23]
	v_pk_fma_f32 v[130:131], v[2:3], v[122:123], v[18:19]
	ds_read_b128 v[120:123], v180 offset:12304
	v_pk_fma_f32 v[124:125], v[4:5], v[124:125], v[20:21]
	v_pk_fma_f32 v[126:127], v[0:1], v[126:127], v[16:17]
	s_waitcnt lgkmcnt(0)
	v_lshlrev_b32_e32 v132, 16, v120
	v_and_b32_e32 v133, 0xffff0000, v120
	v_lshlrev_b32_e32 v120, 16, v121
	v_and_b32_e32 v121, 0xffff0000, v121
	v_lshlrev_b32_e32 v134, 16, v122
	v_and_b32_e32 v135, 0xffff0000, v122
	v_lshlrev_b32_e32 v122, 16, v123
	v_and_b32_e32 v123, 0xffff0000, v123
	v_pk_fma_f32 v[128:129], v[14:15], v[120:121], v[128:129]
	v_pk_fma_f32 v[130:131], v[10:11], v[122:123], v[130:131]
	ds_read_b128 v[120:123], v180 offset:12448
	v_pk_fma_f32 v[124:125], v[12:13], v[132:133], v[124:125]
	v_pk_fma_f32 v[126:127], v[8:9], v[134:135], v[126:127]
	s_waitcnt lgkmcnt(0)
	v_lshlrev_b32_e32 v132, 16, v120
	v_and_b32_e32 v133, 0xffff0000, v120
	v_lshlrev_b32_e32 v120, 16, v121
	v_and_b32_e32 v121, 0xffff0000, v121
	v_lshlrev_b32_e32 v134, 16, v122
	v_and_b32_e32 v135, 0xffff0000, v122
	v_lshlrev_b32_e32 v122, 16, v123
	v_and_b32_e32 v123, 0xffff0000, v123
	v_pk_fma_f32 v[124:125], v[24:25], v[132:133], v[124:125]
	v_pk_fma_f32 v[128:129], v[26:27], v[120:121], v[128:129]
	v_pk_fma_f32 v[132:133], v[28:29], v[134:135], v[126:127]
	v_pk_fma_f32 v[126:127], v[30:31], v[122:123], v[130:131]
	ds_read_b128 v[120:123], v180 offset:12592
	s_waitcnt lgkmcnt(0)
	v_lshlrev_b32_e32 v130, 16, v120
	v_and_b32_e32 v131, 0xffff0000, v120
	v_lshlrev_b32_e32 v120, 16, v121
	v_and_b32_e32 v121, 0xffff0000, v121
	v_lshlrev_b32_e32 v134, 16, v122
	v_and_b32_e32 v135, 0xffff0000, v122
	v_lshlrev_b32_e32 v136, 16, v123
	v_and_b32_e32 v137, 0xffff0000, v123
	v_pk_fma_f32 v[122:123], v[34:35], v[120:121], v[128:129]
	v_pk_fma_f32 v[120:121], v[32:33], v[130:131], v[124:125]
	v_pk_fma_f32 v[126:127], v[38:39], v[136:137], v[126:127]
	v_pk_fma_f32 v[124:125], v[36:37], v[134:135], v[132:133]
	ds_write_b128 v179, v[120:123] offset:4480
	ds_write_b128 v179, v[124:127] offset:4496
	v_cvt_pk_bf16_f32 v120, v120, v121
	v_cvt_pk_bf16_f32 v121, v122, v123
	v_cvt_pk_bf16_f32 v122, v124, v125
	v_cvt_pk_bf16_f32 v123, v126, v127
	ds_write_b128 v180, v[120:123] offset:1152
	s_waitcnt lgkmcnt(0)
	s_mov_b32 s0, 0x37d00d01
	s_mov_b32 s1, 0x37d00d01
	s_mov_b32 s80, 0x3ab60b61
	s_mov_b32 s81, 0x3ab60b61
	s_mov_b32 s82, 0x3c088889
	s_mov_b32 s83, 0x3c088889
	s_mov_b32 s84, 0x3d2aaaab
	s_mov_b32 s85, 0x3d2aaaab
	ds_read_b128 v[120:123], v173
	ds_read_b128 v[222:225], v173 offset:64
	v_mov_b32_e32 v168, 1.0
	v_mov_b32_e32 v232, 0xbfb8aa3b
	v_add_u32_e32 v233, 2304, v175
	s_waitcnt lgkmcnt(0)
	v_mfma_f32_16x16x32_bf16 v[128:131], v[120:123], v[40:43], 0
	v_mfma_f32_16x16x32_bf16 v[132:135], v[120:123], v[72:75], 0
	v_mfma_f32_16x16x32_bf16 v[128:131], v[222:225], v[44:47], v[128:131]
	v_mfma_f32_16x16x32_bf16 v[132:135], v[222:225], v[76:79], v[132:135]
	v_mfma_f32_16x16x32_bf16 v[136:139], v[120:123], v[48:51], 0
	v_mfma_f32_16x16x32_bf16 v[140:143], v[120:123], v[80:83], 0
	v_mfma_f32_16x16x32_bf16 v[136:139], v[222:225], v[52:55], v[136:139]
	v_mfma_f32_16x16x32_bf16 v[140:143], v[222:225], v[84:87], v[140:143]
	s_nop 7
	ds_read2_b32 v[230:231], v233 offset0:0 offset1:68
	v_add_f32_e64 v124, v128, v161
	v_add_f32_e64 v125, v129, v161
	v_add_f32_e64 v126, v132, v163
	v_add_f32_e64 v127, v133, v163
	v_pk_mul_f32 v[124:125], v[124:125], v[232:233] op_sel_hi:[1,0]
	v_pk_mul_f32 v[126:127], v[126:127], v[232:233] op_sel_hi:[1,0]
	v_exp_f32_e32 v124, v124
	v_exp_f32_e32 v125, v125
	v_exp_f32_e32 v126, v126
	v_exp_f32_e32 v127, v127
	v_pk_add_f32 v[124:125], v[124:125], v[168:169] op_sel_hi:[1,0]
	v_pk_add_f32 v[126:127], v[126:127], v[168:169] op_sel_hi:[1,0]
	v_rcp_f32_e32 v124, v124
	v_rcp_f32_e32 v125, v125
	v_rcp_f32_e32 v126, v126
	v_rcp_f32_e32 v127, v127
	v_pk_mul_f32 v[170:171], v[124:125], v[98:99] op_sel_hi:[1,0]
	v_mul_f32_e32 v226, 0x3fb8aa3b, v170
	v_mul_f32_e32 v227, 0x3fb8aa3b, v171
	v_pk_add_f32 v[170:171], v[170:171], v[170:171]
	v_exp_f32_e32 v226, v226
	v_exp_f32_e32 v227, v227
	v_pk_fma_f32 v[228:229], v[170:171], s[0:1], v[198:199] op_sel_hi:[1,1,0]
	v_pk_fma_f32 v[228:229], v[170:171], v[228:229], s[80:81]
	v_pk_fma_f32 v[228:229], v[170:171], v[228:229], s[82:83]
	v_pk_fma_f32 v[228:229], v[170:171], v[228:229], s[84:85]
	v_fmaak_f32 v228, v170, v228, 0x3e2aaaab
	v_fmaak_f32 v229, v171, v229, 0x3e2aaaab
	v_fma_f32 v228, v170, v228, 0.5
	v_fma_f32 v229, v171, v229, 0.5
	v_pk_fma_f32 v[228:229], v[170:171], v[228:229], v[168:169] op_sel_hi:[1,1,0]
	v_pk_mul_f32 v[228:229], v[170:171], v[228:229] neg_lo:[0,1] neg_hi:[0,1]
	v_max_f32_e32 v228, 0, v228
	v_max_f32_e32 v229, 0, v229
	v_sqrt_f32_e32 v228, v228
	v_sqrt_f32_e32 v229, v229
	ds_write_b32 v175, v226 offset:6656
	ds_write_b32 v175, v227 offset:6928
	v_pk_mul_f32 v[228:229], v[126:127], v[228:229]
	s_waitcnt lgkmcnt(2)
	v_pk_mul_f32 v[228:229], v[230:231], v[228:229]
	ds_write2_b32 v233, v228, v229 offset0:0 offset1:68
	ds_read2_b32 v[230:231], v233 offset0:136 offset1:204
	v_add_f32_e64 v124, v130, v161
	v_add_f32_e64 v125, v131, v161
	v_add_f32_e64 v126, v134, v163
	v_add_f32_e64 v127, v135, v163
	v_pk_mul_f32 v[124:125], v[124:125], v[232:233] op_sel_hi:[1,0]
	v_pk_mul_f32 v[126:127], v[126:127], v[232:233] op_sel_hi:[1,0]
	v_exp_f32_e32 v124, v124
	v_exp_f32_e32 v125, v125
	v_exp_f32_e32 v126, v126
	v_exp_f32_e32 v127, v127
	v_pk_add_f32 v[124:125], v[124:125], v[168:169] op_sel_hi:[1,0]
	v_pk_add_f32 v[126:127], v[126:127], v[168:169] op_sel_hi:[1,0]
	v_rcp_f32_e32 v124, v124
	v_rcp_f32_e32 v125, v125
	v_rcp_f32_e32 v126, v126
	v_rcp_f32_e32 v127, v127
	v_pk_mul_f32 v[170:171], v[124:125], v[98:99] op_sel_hi:[1,0]
	v_mul_f32_e32 v226, 0x3fb8aa3b, v170
	v_mul_f32_e32 v227, 0x3fb8aa3b, v171
	v_pk_add_f32 v[170:171], v[170:171], v[170:171]
	v_exp_f32_e32 v226, v226
	v_exp_f32_e32 v227, v227
	v_pk_fma_f32 v[228:229], v[170:171], s[0:1], v[198:199] op_sel_hi:[1,1,0]
	v_pk_fma_f32 v[228:229], v[170:171], v[228:229], s[80:81]
	v_pk_fma_f32 v[228:229], v[170:171], v[228:229], s[82:83]
	v_pk_fma_f32 v[228:229], v[170:171], v[228:229], s[84:85]
	v_fmaak_f32 v228, v170, v228, 0x3e2aaaab
	v_fmaak_f32 v229, v171, v229, 0x3e2aaaab
	v_fma_f32 v228, v170, v228, 0.5
	v_fma_f32 v229, v171, v229, 0.5
	v_pk_fma_f32 v[228:229], v[170:171], v[228:229], v[168:169] op_sel_hi:[1,1,0]
	v_pk_mul_f32 v[228:229], v[170:171], v[228:229] neg_lo:[0,1] neg_hi:[0,1]
	v_max_f32_e32 v228, 0, v228
	v_max_f32_e32 v229, 0, v229
	v_sqrt_f32_e32 v228, v228
	v_sqrt_f32_e32 v229, v229
	ds_write_b32 v175, v226 offset:7200
	ds_write_b32 v175, v227 offset:7472
	v_pk_mul_f32 v[228:229], v[126:127], v[228:229]
	s_waitcnt lgkmcnt(2)
	v_pk_mul_f32 v[228:229], v[230:231], v[228:229]
	ds_write2_b32 v233, v228, v229 offset0:136 offset1:204
	v_mfma_f32_16x16x32_bf16 v[128:131], v[120:123], v[56:59], 0
	v_mfma_f32_16x16x32_bf16 v[132:135], v[120:123], v[88:91], 0
	v_mfma_f32_16x16x32_bf16 v[128:131], v[222:225], v[60:63], v[128:131]
	v_mfma_f32_16x16x32_bf16 v[132:135], v[222:225], v[92:95], v[132:135]
	ds_read2_b32 v[230:231], v233 offset0:16 offset1:84
	v_add_f32_e64 v124, v136, v181
	v_add_f32_e64 v125, v137, v181
	v_pk_add_f32 v[126:127], v[140:141], v[188:189] op_sel_hi:[1,0]
	v_pk_mul_f32 v[124:125], v[124:125], v[232:233] op_sel_hi:[1,0]
	v_pk_mul_f32 v[126:127], v[126:127], v[232:233] op_sel_hi:[1,0]
	v_exp_f32_e32 v124, v124
	v_exp_f32_e32 v125, v125
	v_exp_f32_e32 v126, v126
	v_exp_f32_e32 v127, v127
	v_pk_add_f32 v[124:125], v[124:125], v[168:169] op_sel_hi:[1,0]
	v_pk_add_f32 v[126:127], v[126:127], v[168:169] op_sel_hi:[1,0]
	v_rcp_f32_e32 v124, v124
	v_rcp_f32_e32 v125, v125
	v_rcp_f32_e32 v126, v126
	v_rcp_f32_e32 v127, v127
	v_mul_f32_e64 v170, v124, v193
	v_mul_f32_e64 v171, v125, v193
	v_mul_f32_e32 v226, 0x3fb8aa3b, v170
	v_mul_f32_e32 v227, 0x3fb8aa3b, v171
	v_pk_add_f32 v[170:171], v[170:171], v[170:171]
	v_exp_f32_e32 v226, v226
	v_exp_f32_e32 v227, v227
	v_pk_fma_f32 v[228:229], v[170:171], s[0:1], v[198:199] op_sel_hi:[1,1,0]
	v_pk_fma_f32 v[228:229], v[170:171], v[228:229], s[80:81]
	v_pk_fma_f32 v[228:229], v[170:171], v[228:229], s[82:83]
	v_pk_fma_f32 v[228:229], v[170:171], v[228:229], s[84:85]
	v_fmaak_f32 v228, v170, v228, 0x3e2aaaab
	v_fmaak_f32 v229, v171, v229, 0x3e2aaaab
	v_fma_f32 v228, v170, v228, 0.5
	v_fma_f32 v229, v171, v229, 0.5
	v_pk_fma_f32 v[228:229], v[170:171], v[228:229], v[168:169] op_sel_hi:[1,1,0]
	v_pk_mul_f32 v[228:229], v[170:171], v[228:229] neg_lo:[0,1] neg_hi:[0,1]
	v_max_f32_e32 v228, 0, v228
	v_max_f32_e32 v229, 0, v229
	v_sqrt_f32_e32 v228, v228
	v_sqrt_f32_e32 v229, v229
	ds_write_b32 v175, v226 offset:6720
	ds_write_b32 v175, v227 offset:6992
	v_pk_mul_f32 v[228:229], v[126:127], v[228:229]
	s_waitcnt lgkmcnt(2)
	v_pk_mul_f32 v[228:229], v[230:231], v[228:229]
	ds_write2_b32 v233, v228, v229 offset0:16 offset1:84
	ds_read2_b32 v[230:231], v233 offset0:152 offset1:220
	v_add_f32_e64 v124, v138, v181
	v_add_f32_e64 v125, v139, v181
	v_pk_add_f32 v[126:127], v[142:143], v[188:189] op_sel_hi:[1,0]
	v_pk_mul_f32 v[124:125], v[124:125], v[232:233] op_sel_hi:[1,0]
	v_pk_mul_f32 v[126:127], v[126:127], v[232:233] op_sel_hi:[1,0]
	v_exp_f32_e32 v124, v124
	v_exp_f32_e32 v125, v125
	v_exp_f32_e32 v126, v126
	v_exp_f32_e32 v127, v127
	v_pk_add_f32 v[124:125], v[124:125], v[168:169] op_sel_hi:[1,0]
	v_pk_add_f32 v[126:127], v[126:127], v[168:169] op_sel_hi:[1,0]
	v_rcp_f32_e32 v124, v124
	v_rcp_f32_e32 v125, v125
	v_rcp_f32_e32 v126, v126
	v_rcp_f32_e32 v127, v127
	v_mul_f32_e64 v170, v124, v193
	v_mul_f32_e64 v171, v125, v193
	v_mul_f32_e32 v226, 0x3fb8aa3b, v170
	v_mul_f32_e32 v227, 0x3fb8aa3b, v171
	v_pk_add_f32 v[170:171], v[170:171], v[170:171]
	v_exp_f32_e32 v226, v226
	v_exp_f32_e32 v227, v227
	v_pk_fma_f32 v[228:229], v[170:171], s[0:1], v[198:199] op_sel_hi:[1,1,0]
	v_pk_fma_f32 v[228:229], v[170:171], v[228:229], s[80:81]
	v_pk_fma_f32 v[228:229], v[170:171], v[228:229], s[82:83]
	v_pk_fma_f32 v[228:229], v[170:171], v[228:229], s[84:85]
	v_fmaak_f32 v228, v170, v228, 0x3e2aaaab
	v_fmaak_f32 v229, v171, v229, 0x3e2aaaab
	v_fma_f32 v228, v170, v228, 0.5
	v_fma_f32 v229, v171, v229, 0.5
	v_pk_fma_f32 v[228:229], v[170:171], v[228:229], v[168:169] op_sel_hi:[1,1,0]
	v_pk_mul_f32 v[228:229], v[170:171], v[228:229] neg_lo:[0,1] neg_hi:[0,1]
	v_max_f32_e32 v228, 0, v228
	v_max_f32_e32 v229, 0, v229
	v_sqrt_f32_e32 v228, v228
	v_sqrt_f32_e32 v229, v229
	ds_write_b32 v175, v226 offset:7264
	ds_write_b32 v175, v227 offset:7536
	v_pk_mul_f32 v[228:229], v[126:127], v[228:229]
	s_waitcnt lgkmcnt(2)
	v_pk_mul_f32 v[228:229], v[230:231], v[228:229]
	ds_write2_b32 v233, v228, v229 offset0:152 offset1:220
	v_mfma_f32_16x16x32_bf16 v[136:139], v[120:123], v[64:67], 0
	v_mfma_f32_16x16x32_bf16 v[140:143], v[120:123], v[100:103], 0
	v_mfma_f32_16x16x32_bf16 v[136:139], v[222:225], v[68:71], v[136:139]
	v_mfma_f32_16x16x32_bf16 v[140:143], v[222:225], v[104:107], v[140:143]
	ds_read2_b32 v[230:231], v233 offset0:32 offset1:100
	v_add_f32_e64 v124, v128, v189
	v_add_f32_e64 v125, v129, v189
	v_pk_add_f32 v[126:127], v[132:133], v[190:191] op_sel_hi:[1,0]
	v_pk_mul_f32 v[124:125], v[124:125], v[232:233] op_sel_hi:[1,0]
	v_pk_mul_f32 v[126:127], v[126:127], v[232:233] op_sel_hi:[1,0]
	v_exp_f32_e32 v124, v124
	v_exp_f32_e32 v125, v125
	v_exp_f32_e32 v126, v126
	v_exp_f32_e32 v127, v127
	v_pk_add_f32 v[124:125], v[124:125], v[168:169] op_sel_hi:[1,0]
	v_pk_add_f32 v[126:127], v[126:127], v[168:169] op_sel_hi:[1,0]
	v_rcp_f32_e32 v124, v124
	v_rcp_f32_e32 v125, v125
	v_rcp_f32_e32 v126, v126
	v_rcp_f32_e32 v127, v127
	v_pk_mul_f32 v[170:171], v[124:125], v[220:221] op_sel_hi:[1,0]
	v_mul_f32_e32 v226, 0x3fb8aa3b, v170
	v_mul_f32_e32 v227, 0x3fb8aa3b, v171
	v_pk_add_f32 v[170:171], v[170:171], v[170:171]
	v_exp_f32_e32 v226, v226
	v_exp_f32_e32 v227, v227
	v_pk_fma_f32 v[228:229], v[170:171], s[0:1], v[198:199] op_sel_hi:[1,1,0]
	v_pk_fma_f32 v[228:229], v[170:171], v[228:229], s[80:81]
	v_pk_fma_f32 v[228:229], v[170:171], v[228:229], s[82:83]
	v_pk_fma_f32 v[228:229], v[170:171], v[228:229], s[84:85]
	v_fmaak_f32 v228, v170, v228, 0x3e2aaaab
	v_fmaak_f32 v229, v171, v229, 0x3e2aaaab
	v_fma_f32 v228, v170, v228, 0.5
	v_fma_f32 v229, v171, v229, 0.5
	v_pk_fma_f32 v[228:229], v[170:171], v[228:229], v[168:169] op_sel_hi:[1,1,0]
	v_pk_mul_f32 v[228:229], v[170:171], v[228:229] neg_lo:[0,1] neg_hi:[0,1]
	v_max_f32_e32 v228, 0, v228
	v_max_f32_e32 v229, 0, v229
	v_sqrt_f32_e32 v228, v228
	v_sqrt_f32_e32 v229, v229
	ds_write_b32 v175, v226 offset:6784
	ds_write_b32 v175, v227 offset:7056
	v_pk_mul_f32 v[228:229], v[126:127], v[228:229]
	s_waitcnt lgkmcnt(2)
	v_pk_mul_f32 v[228:229], v[230:231], v[228:229]
	ds_write2_b32 v233, v228, v229 offset0:32 offset1:100
	ds_read2_b32 v[230:231], v233 offset0:168 offset1:236
	v_add_f32_e64 v124, v130, v189
	v_add_f32_e64 v125, v131, v189
	v_pk_add_f32 v[126:127], v[134:135], v[190:191] op_sel_hi:[1,0]
	v_pk_mul_f32 v[124:125], v[124:125], v[232:233] op_sel_hi:[1,0]
	v_pk_mul_f32 v[126:127], v[126:127], v[232:233] op_sel_hi:[1,0]
	v_exp_f32_e32 v124, v124
	v_exp_f32_e32 v125, v125
	v_exp_f32_e32 v126, v126
	v_exp_f32_e32 v127, v127
	v_pk_add_f32 v[124:125], v[124:125], v[168:169] op_sel_hi:[1,0]
	v_pk_add_f32 v[126:127], v[126:127], v[168:169] op_sel_hi:[1,0]
	v_rcp_f32_e32 v124, v124
	v_rcp_f32_e32 v125, v125
	v_rcp_f32_e32 v126, v126
	v_rcp_f32_e32 v127, v127
	v_pk_mul_f32 v[170:171], v[124:125], v[220:221] op_sel_hi:[1,0]
	v_mul_f32_e32 v226, 0x3fb8aa3b, v170
	v_mul_f32_e32 v227, 0x3fb8aa3b, v171
	v_pk_add_f32 v[170:171], v[170:171], v[170:171]
	v_exp_f32_e32 v226, v226
	v_exp_f32_e32 v227, v227
	v_pk_fma_f32 v[228:229], v[170:171], s[0:1], v[198:199] op_sel_hi:[1,1,0]
	v_pk_fma_f32 v[228:229], v[170:171], v[228:229], s[80:81]
	v_pk_fma_f32 v[228:229], v[170:171], v[228:229], s[82:83]
	v_pk_fma_f32 v[228:229], v[170:171], v[228:229], s[84:85]
	v_fmaak_f32 v228, v170, v228, 0x3e2aaaab
	v_fmaak_f32 v229, v171, v229, 0x3e2aaaab
	v_fma_f32 v228, v170, v228, 0.5
	v_fma_f32 v229, v171, v229, 0.5
	v_pk_fma_f32 v[228:229], v[170:171], v[228:229], v[168:169] op_sel_hi:[1,1,0]
	v_pk_mul_f32 v[228:229], v[170:171], v[228:229] neg_lo:[0,1] neg_hi:[0,1]
	v_max_f32_e32 v228, 0, v228
	v_max_f32_e32 v229, 0, v229
	v_sqrt_f32_e32 v228, v228
	v_sqrt_f32_e32 v229, v229
	ds_write_b32 v175, v226 offset:7328
	ds_write_b32 v175, v227 offset:7600
	v_pk_mul_f32 v[228:229], v[126:127], v[228:229]
	s_waitcnt lgkmcnt(2)
	v_pk_mul_f32 v[228:229], v[230:231], v[228:229]
	ds_write2_b32 v233, v228, v229 offset0:168 offset1:236
	ds_read2_b32 v[230:231], v233 offset0:48 offset1:116
	v_pk_add_f32 v[124:125], v[136:137], v[192:193] op_sel_hi:[1,0]
	v_add_f32_e64 v126, v140, v191
	v_add_f32_e64 v127, v141, v191
	v_pk_mul_f32 v[124:125], v[124:125], v[232:233] op_sel_hi:[1,0]
	v_pk_mul_f32 v[126:127], v[126:127], v[232:233] op_sel_hi:[1,0]
	v_exp_f32_e32 v124, v124
	v_exp_f32_e32 v125, v125
	v_exp_f32_e32 v126, v126
	v_exp_f32_e32 v127, v127
	v_pk_add_f32 v[124:125], v[124:125], v[168:169] op_sel_hi:[1,0]
	v_pk_add_f32 v[126:127], v[126:127], v[168:169] op_sel_hi:[1,0]
	v_rcp_f32_e32 v124, v124
	v_rcp_f32_e32 v125, v125
	v_rcp_f32_e32 v126, v126
	v_rcp_f32_e32 v127, v127
	v_mul_f32_e64 v170, v124, v221
	v_mul_f32_e64 v171, v125, v221
	v_mul_f32_e32 v226, 0x3fb8aa3b, v170
	v_mul_f32_e32 v227, 0x3fb8aa3b, v171
	v_pk_add_f32 v[170:171], v[170:171], v[170:171]
	v_exp_f32_e32 v226, v226
	v_exp_f32_e32 v227, v227
	v_pk_fma_f32 v[228:229], v[170:171], s[0:1], v[198:199] op_sel_hi:[1,1,0]
	v_pk_fma_f32 v[228:229], v[170:171], v[228:229], s[80:81]
	v_pk_fma_f32 v[228:229], v[170:171], v[228:229], s[82:83]
	v_pk_fma_f32 v[228:229], v[170:171], v[228:229], s[84:85]
	v_fmaak_f32 v228, v170, v228, 0x3e2aaaab
	v_fmaak_f32 v229, v171, v229, 0x3e2aaaab
	v_fma_f32 v228, v170, v228, 0.5
	v_fma_f32 v229, v171, v229, 0.5
	v_pk_fma_f32 v[228:229], v[170:171], v[228:229], v[168:169] op_sel_hi:[1,1,0]
	v_pk_mul_f32 v[228:229], v[170:171], v[228:229] neg_lo:[0,1] neg_hi:[0,1]
	v_max_f32_e32 v228, 0, v228
	v_max_f32_e32 v229, 0, v229
	v_sqrt_f32_e32 v228, v228
	v_sqrt_f32_e32 v229, v229
	ds_write_b32 v175, v226 offset:6848
	ds_write_b32 v175, v227 offset:7120
	v_pk_mul_f32 v[228:229], v[126:127], v[228:229]
	s_waitcnt lgkmcnt(2)
	v_pk_mul_f32 v[228:229], v[230:231], v[228:229]
	ds_write2_b32 v233, v228, v229 offset0:48 offset1:116
	ds_read2_b32 v[230:231], v233 offset0:184 offset1:252
	v_pk_add_f32 v[124:125], v[138:139], v[192:193] op_sel_hi:[1,0]
	v_add_f32_e64 v126, v142, v191
	v_add_f32_e64 v127, v143, v191
	v_pk_mul_f32 v[124:125], v[124:125], v[232:233] op_sel_hi:[1,0]
	v_pk_mul_f32 v[126:127], v[126:127], v[232:233] op_sel_hi:[1,0]
	v_exp_f32_e32 v124, v124
	v_exp_f32_e32 v125, v125
	v_exp_f32_e32 v126, v126
	v_exp_f32_e32 v127, v127
	v_pk_add_f32 v[124:125], v[124:125], v[168:169] op_sel_hi:[1,0]
	v_pk_add_f32 v[126:127], v[126:127], v[168:169] op_sel_hi:[1,0]
	v_rcp_f32_e32 v124, v124
	v_rcp_f32_e32 v125, v125
	v_rcp_f32_e32 v126, v126
	v_rcp_f32_e32 v127, v127
	v_mul_f32_e64 v170, v124, v221
	v_mul_f32_e64 v171, v125, v221
	v_mul_f32_e32 v226, 0x3fb8aa3b, v170
	v_mul_f32_e32 v227, 0x3fb8aa3b, v171
	v_pk_add_f32 v[170:171], v[170:171], v[170:171]
	v_exp_f32_e32 v226, v226
	v_exp_f32_e32 v227, v227
	v_pk_fma_f32 v[228:229], v[170:171], s[0:1], v[198:199] op_sel_hi:[1,1,0]
	v_pk_fma_f32 v[228:229], v[170:171], v[228:229], s[80:81]
	v_pk_fma_f32 v[228:229], v[170:171], v[228:229], s[82:83]
	v_pk_fma_f32 v[228:229], v[170:171], v[228:229], s[84:85]
	v_fmaak_f32 v228, v170, v228, 0x3e2aaaab
	v_fmaak_f32 v229, v171, v229, 0x3e2aaaab
	v_fma_f32 v228, v170, v228, 0.5
	v_fma_f32 v229, v171, v229, 0.5
	v_pk_fma_f32 v[228:229], v[170:171], v[228:229], v[168:169] op_sel_hi:[1,1,0]
	v_pk_mul_f32 v[228:229], v[170:171], v[228:229] neg_lo:[0,1] neg_hi:[0,1]
	v_max_f32_e32 v228, 0, v228
	v_max_f32_e32 v229, 0, v229
	v_sqrt_f32_e32 v228, v228
	v_sqrt_f32_e32 v229, v229
	ds_write_b32 v175, v226 offset:7392
	ds_write_b32 v175, v227 offset:7664
	v_pk_mul_f32 v[228:229], v[126:127], v[228:229]
	s_waitcnt lgkmcnt(2)
	v_pk_mul_f32 v[228:229], v[230:231], v[228:229]
	ds_write2_b32 v233, v228, v229 offset0:184 offset1:252
	v_add_u32_e32 v126, 0x1c00, v174
	s_waitcnt lgkmcnt(0)
	v_add_u32_e32 v165, 6656, v174
	v_add_u32_e32 v168, 2304, v174
	ds_read2_b32 v[120:121], v165 offset0:0 offset1:68
	ds_read2_b32 v[122:123], v168 offset0:0 offset1:68
	ds_read2_b32 v[124:125], v165 offset0:136 offset1:204
	ds_read2_b32 v[126:127], v168 offset0:136 offset1:204
	v_add_u32_e32 v165, 7744, v174
	v_add_u32_e32 v168, 3392, v174
	ds_read2_b32 v[128:129], v165 offset0:0 offset1:68
	ds_read2_b32 v[130:131], v168 offset0:0 offset1:68
	ds_read2_b32 v[132:133], v165 offset0:136 offset1:204
	ds_read2_b32 v[134:135], v168 offset0:136 offset1:204
	v_add_u32_e32 v165, 8832, v174
	v_add_u32_e32 v168, 4480, v174
	ds_read2_b32 v[136:137], v165 offset0:0 offset1:68
	ds_read2_b32 v[138:139], v168 offset0:0 offset1:68
	ds_read2_b32 v[140:141], v165 offset0:136 offset1:204
	ds_read2_b32 v[142:143], v168 offset0:136 offset1:204
	v_add_u32_e32 v165, 9920, v174
	v_add_u32_e32 v168, 5568, v174
	ds_read2_b32 v[170:171], v165 offset0:0 offset1:68
	ds_read2_b32 v[222:223], v168 offset0:0 offset1:68
	ds_read2_b32 v[224:225], v165 offset0:136 offset1:204
	ds_read2_b32 v[226:227], v168 offset0:136 offset1:204
	s_waitcnt lgkmcnt(14)
	v_fma_f32 v164, v164, v120, v122
	v_mul_f32_e32 v169, v169, v120
	v_fma_f32 v164, v164, v121, v123
	v_mul_f32_e32 v169, v169, v121
	s_waitcnt lgkmcnt(12)
	v_fma_f32 v164, v164, v124, v126
	v_mul_f32_e32 v169, v169, v124
	v_fma_f32 v164, v164, v125, v127
	v_mul_f32_e32 v169, v169, v125
	s_waitcnt lgkmcnt(10)
	v_fma_f32 v164, v164, v128, v130
	v_mul_f32_e32 v169, v169, v128
	v_fma_f32 v164, v164, v129, v131
	v_mul_f32_e32 v169, v169, v129
	s_waitcnt lgkmcnt(8)
	v_fma_f32 v164, v164, v132, v134
	v_mul_f32_e32 v169, v169, v132
	v_fma_f32 v164, v164, v133, v135
	v_mul_f32_e32 v169, v169, v133
	s_waitcnt lgkmcnt(6)
	v_fma_f32 v164, v164, v136, v138
	v_mul_f32_e32 v169, v169, v136
	v_fma_f32 v164, v164, v137, v139
	v_mul_f32_e32 v169, v169, v137
	s_waitcnt lgkmcnt(4)
	v_fma_f32 v164, v164, v140, v142
	v_mul_f32_e32 v169, v169, v140
	v_fma_f32 v164, v164, v141, v143
	v_mul_f32_e32 v169, v169, v141
	s_waitcnt lgkmcnt(2)
	v_fma_f32 v164, v164, v170, v222
	v_mul_f32_e32 v169, v169, v170
	v_fma_f32 v164, v164, v171, v223
	v_mul_f32_e32 v169, v169, v171
	s_waitcnt lgkmcnt(0)
	v_fma_f32 v164, v164, v224, v226
	v_mul_f32_e32 v169, v169, v224
	v_fma_f32 v164, v164, v225, v227
	v_mul_f32_e32 v169, v169, v225
	s_cbranch_scc0 .LBB0_194
